# m3_prompt last-chunk conv-state copies: all loads of a part issued up front (were 12 dependent round trips)
# speedup vs baseline: 1.0166x; 1.0014x over previous
.LBB0_150:
	v_readlane_b32 s84, v252, 39
	s_cmp_lg_u32 s41, 31
	v_readlane_b32 s85, v252, 40
	s_cbranch_scc1 .LBB0_104
	s_and_saveexec_b64 s[24:25], s[18:19]
	s_cbranch_execz .LBB0_159
	v_readlane_b32 s4, v253, 11
	s_lshl_b32 s26, s20, 11
	s_or_b32 s26, s26, 0x7fd
	v_lshlrev_b32_e32 v0, 1, v160
	v_lshlrev_b32_e32 v1, 2, v160
	s_mul_i32 s27, s26, 0x4200
	s_add_u32 s28, s4, s20
	s_mul_i32 s28, s28, 3
	s_add_u32 s34, s70, s27
	s_addc_u32 s35, s71, 0
	s_lshl_b32 s29, s28, 12
	s_add_u32 s36, s72, s29
	s_addc_u32 s37, s73, 0
	s_add_u32 s36, s36, 0x40a0000
	s_addc_u32 s37, s37, 0
	global_load_ushort v212, v0, s[34:35]
	global_load_ushort v213, v0, s[34:35] offset:1024
	s_add_u32 s34, s34, 0x4200
	s_addc_u32 s35, s35, 0
	global_load_ushort v214, v0, s[34:35]
	global_load_ushort v215, v0, s[34:35] offset:1024
	s_add_u32 s34, s34, 0x4200
	s_addc_u32 s35, s35, 0
	global_load_ushort v216, v0, s[34:35]
	global_load_ushort v217, v0, s[34:35] offset:1024
	s_waitcnt vmcnt(0)
	v_lshlrev_b32_e32 v212, 16, v212
	v_lshlrev_b32_e32 v213, 16, v213
	v_lshlrev_b32_e32 v214, 16, v214
	v_lshlrev_b32_e32 v215, 16, v215
	v_lshlrev_b32_e32 v216, 16, v216
	v_lshlrev_b32_e32 v217, 16, v217
	global_store_dword v1, v212, s[36:37]
	global_store_dword v1, v213, s[36:37] offset:2048
	s_add_u32 s36, s36, 0x1000
	s_addc_u32 s37, s37, 0
	global_store_dword v1, v214, s[36:37]
	global_store_dword v1, v215, s[36:37] offset:2048
	s_add_u32 s36, s36, 0x1000
	s_addc_u32 s37, s37, 0
	global_store_dword v1, v216, s[36:37]
	global_store_dword v1, v217, s[36:37] offset:2048
.LBB0_159:
	s_or_b64 exec, exec, s[24:25]
	s_and_saveexec_b64 s[24:25], s[16:17]
	s_cbranch_execz .LBB0_103
	v_readlane_b32 s4, v253, 11
	s_lshl_b32 s26, s20, 11
	s_or_b32 s26, s26, 0x7fd
	v_lshlrev_b32_e32 v0, 1, v160
	v_lshlrev_b32_e32 v1, 2, v160
	s_mul_i32 s27, s26, 0x4200
	s_add_u32 s28, s4, s20
	s_mul_i32 s28, s28, 3
	s_add_u32 s34, s70, s27
	s_addc_u32 s35, s71, 0
	s_add_u32 s34, s34, 0x1000
	s_addc_u32 s35, s35, 0
	s_add_u32 s36, s34, 0x1000
	s_addc_u32 s37, s35, 0
	s_mul_i32 s29, s28, 0x3000
	s_add_u32 s38, s72, s29
	s_addc_u32 s39, s73, 0
	s_add_u32 s38, s38, 0x5100000
	s_addc_u32 s39, s39, 0
	global_load_ushort v212, v0, s[34:35]
	global_load_ushort v213, v0, s[34:35] offset:1024
	global_load_ushort v214, v0, s[34:35] offset:2048
	global_load_ushort v215, v0, s[34:35] offset:3072
	global_load_ushort v216, v0, s[36:37]
	global_load_ushort v217, v0, s[36:37] offset:1024
	s_add_u32 s34, s34, 0x4200
	s_addc_u32 s35, s35, 0
	s_add_u32 s36, s36, 0x4200
	s_addc_u32 s37, s37, 0
	global_load_ushort v218, v0, s[34:35]
	global_load_ushort v219, v0, s[34:35] offset:1024
	global_load_ushort v220, v0, s[34:35] offset:2048
	global_load_ushort v221, v0, s[34:35] offset:3072
	global_load_ushort v222, v0, s[36:37]
	global_load_ushort v223, v0, s[36:37] offset:1024
	s_add_u32 s34, s34, 0x4200
	s_addc_u32 s35, s35, 0
	s_add_u32 s36, s36, 0x4200
	s_addc_u32 s37, s37, 0
	global_load_ushort v224, v0, s[34:35]
	global_load_ushort v225, v0, s[34:35] offset:1024
	global_load_ushort v226, v0, s[34:35] offset:2048
	global_load_ushort v227, v0, s[34:35] offset:3072
	global_load_ushort v228, v0, s[36:37]
	global_load_ushort v229, v0, s[36:37] offset:1024
	s_waitcnt vmcnt(0)
	v_lshlrev_b32_e32 v212, 16, v212
	v_lshlrev_b32_e32 v213, 16, v213
	v_lshlrev_b32_e32 v214, 16, v214
	v_lshlrev_b32_e32 v215, 16, v215
	v_lshlrev_b32_e32 v216, 16, v216
	v_lshlrev_b32_e32 v217, 16, v217
	v_lshlrev_b32_e32 v218, 16, v218
	v_lshlrev_b32_e32 v219, 16, v219
	v_lshlrev_b32_e32 v220, 16, v220
	v_lshlrev_b32_e32 v221, 16, v221
	v_lshlrev_b32_e32 v222, 16, v222
	v_lshlrev_b32_e32 v223, 16, v223
	v_lshlrev_b32_e32 v224, 16, v224
	v_lshlrev_b32_e32 v225, 16, v225
	v_lshlrev_b32_e32 v226, 16, v226
	v_lshlrev_b32_e32 v227, 16, v227
	v_lshlrev_b32_e32 v228, 16, v228
	v_lshlrev_b32_e32 v229, 16, v229
	global_store_dword v1, v212, s[38:39]
	global_store_dword v1, v213, s[38:39] offset:2048
	s_add_u32 s38, s38, 0x1000
	s_addc_u32 s39, s39, 0
	global_store_dword v1, v214, s[38:39]
	global_store_dword v1, v215, s[38:39] offset:2048
	s_add_u32 s38, s38, 0x1000
	s_addc_u32 s39, s39, 0
	global_store_dword v1, v216, s[38:39]
	global_store_dword v1, v217, s[38:39] offset:2048
	s_add_u32 s38, s38, 0x1000
	s_addc_u32 s39, s39, 0
	global_store_dword v1, v218, s[38:39]
	global_store_dword v1, v219, s[38:39] offset:2048
	s_add_u32 s38, s38, 0x1000
	s_addc_u32 s39, s39, 0
	global_store_dword v1, v220, s[38:39]
	global_store_dword v1, v221, s[38:39] offset:2048
	s_add_u32 s38, s38, 0x1000
	s_addc_u32 s39, s39, 0
	global_store_dword v1, v222, s[38:39]
	global_store_dword v1, v223, s[38:39] offset:2048
	s_add_u32 s38, s38, 0x1000
	s_addc_u32 s39, s39, 0
	global_store_dword v1, v224, s[38:39]
	global_store_dword v1, v225, s[38:39] offset:2048
	s_add_u32 s38, s38, 0x1000
	s_addc_u32 s39, s39, 0
	global_store_dword v1, v226, s[38:39]
	global_store_dword v1, v227, s[38:39] offset:2048
	s_add_u32 s38, s38, 0x1000
	s_addc_u32 s39, s39, 0
	global_store_dword v1, v228, s[38:39]
	global_store_dword v1, v229, s[38:39] offset:2048
	s_branch .LBB0_103
